# P1 K-loop: first K-tile peeled with SrcC=0, accumulator zeroing pass removed
# speedup vs baseline: 1.0025x; 1.0025x over previous
.LBB0_119:
	s_ashr_i32 s25, s24, 31
	s_lshl_b64 s[26:27], s[24:25], 19
	s_add_u32 s26, s70, s26
	s_addc_u32 s27, s71, s27
	s_and_b64 s[28:29], s[8:9], exec
	s_cselect_b32 s5, s27, s31
	s_cselect_b32 s7, s26, s30
	s_ashr_i32 s23, s22, 31
	s_lshl_b64 s[28:29], s[22:23], 19
	s_add_u32 s28, s2, s28
	s_addc_u32 s29, s3, s29
	s_and_b64 s[36:37], s[8:9], exec
	s_cselect_b32 s23, s29, s35
	s_cselect_b32 s25, s28, s34
	s_add_u32 s30, s30, 0x40080
	s_addc_u32 s31, s31, 0
	s_add_u32 s57, s34, 0x100
	s_addc_u32 s58, s35, 0
	s_mov_b32 s59, -2
	ds_read_b128 v[72:75], v175
	ds_read_b128 v[76:79], v175 offset:1024
	ds_read_b128 v[88:91], v175 offset:2048
	ds_read_b128 v[92:95], v175 offset:3072
	ds_read_b128 v[162:165], v176
	ds_read_b128 v[166:169], v176 offset:1024
	ds_read_b128 v[180:183], v176 offset:2048
	ds_read_b128 v[184:187], v176 offset:3072
	s_add_u32 s34, s30, 0xfffc0080
	s_addc_u32 s35, s31, -1
	s_cmp_eq_u32 s59, 12
	s_cselect_b32 s37, s5, s35
	s_cselect_b32 s36, s7, s34
	s_cselect_b32 s35, s23, s58
	s_cselect_b32 s34, s25, s57
	v_lshl_add_u64 v[170:171], s[30:31], 0, v[154:155]
	s_add_i32 m0, s76, 0xc000
	ds_read_b128 v[188:191], v177
	ds_read_b128 v[192:195], v177 offset:1024
	ds_read_b128 v[198:201], v177 offset:2048
	ds_read_b128 v[202:205], v177 offset:3072
	ds_read_b128 v[206:209], v177 offset:4096
	ds_read_b128 v[210:213], v177 offset:5120
	ds_read_b128 v[214:217], v177 offset:6144
	ds_read_b128 v[218:221], v177 offset:7168
	global_load_lds_dwordx4 v[170:171], off
	v_lshl_add_u64 v[170:171], s[30:31], 0, v[156:157]
	s_add_i32 m0, s76, 0xe000
	s_nop 0
	global_load_lds_dwordx4 v[170:171], off
	s_waitcnt vmcnt(8)
	s_waitcnt lgkmcnt(0)
	s_barrier
	s_setprio 1
	s_waitcnt lgkmcnt(0)
	v_mfma_f32_16x16x32_bf16 v[140:143], v[72:75], v[188:191], 0
	v_mfma_f32_16x16x32_bf16 v[136:139], v[88:91], v[188:191], 0
	v_mfma_f32_16x16x32_bf16 v[124:127], v[72:75], v[198:201], 0
	v_mfma_f32_16x16x32_bf16 v[120:123], v[88:91], v[198:201], 0
	v_mfma_f32_16x16x32_bf16 v[108:111], v[72:75], v[206:209], 0
	v_mfma_f32_16x16x32_bf16 v[104:107], v[88:91], v[206:209], 0
	v_mfma_f32_16x16x32_bf16 v[84:87], v[72:75], v[214:217], 0
	v_mfma_f32_16x16x32_bf16 v[80:83], v[88:91], v[214:217], 0
	v_mfma_f32_16x16x32_bf16 v[140:143], v[76:79], v[192:195], v[140:143]
	v_mfma_f32_16x16x32_bf16 v[136:139], v[92:95], v[192:195], v[136:139]
	v_mfma_f32_16x16x32_bf16 v[124:127], v[76:79], v[202:205], v[124:127]
	v_mfma_f32_16x16x32_bf16 v[120:123], v[92:95], v[202:205], v[120:123]
	v_mfma_f32_16x16x32_bf16 v[108:111], v[76:79], v[210:213], v[108:111]
	v_mfma_f32_16x16x32_bf16 v[104:107], v[92:95], v[210:213], v[104:107]
	v_mfma_f32_16x16x32_bf16 v[84:87], v[76:79], v[218:221], v[84:87]
	v_mfma_f32_16x16x32_bf16 v[80:83], v[92:95], v[218:221], v[80:83]
	s_setprio 0
	s_setprio 1
	v_mfma_f32_16x16x32_bf16 v[132:135], v[162:165], v[188:191], 0
	v_mfma_f32_16x16x32_bf16 v[128:131], v[180:183], v[188:191], 0
	v_mfma_f32_16x16x32_bf16 v[116:119], v[162:165], v[198:201], 0
	v_mfma_f32_16x16x32_bf16 v[112:115], v[180:183], v[198:201], 0
	v_mfma_f32_16x16x32_bf16 v[100:103], v[162:165], v[206:209], 0
	v_mfma_f32_16x16x32_bf16 v[96:99], v[180:183], v[206:209], 0
	v_mfma_f32_16x16x32_bf16 v[68:71], v[162:165], v[214:217], 0
	v_mfma_f32_16x16x32_bf16 v[64:67], v[180:183], v[214:217], 0
	v_mfma_f32_16x16x32_bf16 v[132:135], v[166:169], v[192:195], v[132:135]
	v_mfma_f32_16x16x32_bf16 v[128:131], v[184:187], v[192:195], v[128:131]
	v_mfma_f32_16x16x32_bf16 v[116:119], v[166:169], v[202:205], v[116:119]
	v_mfma_f32_16x16x32_bf16 v[112:115], v[184:187], v[202:205], v[112:115]
	v_mfma_f32_16x16x32_bf16 v[100:103], v[166:169], v[210:213], v[100:103]
	v_mfma_f32_16x16x32_bf16 v[96:99], v[184:187], v[210:213], v[96:99]
	v_mfma_f32_16x16x32_bf16 v[68:71], v[166:169], v[218:221], v[68:71]
	v_mfma_f32_16x16x32_bf16 v[64:67], v[184:187], v[218:221], v[64:67]
	s_setprio 0
	s_barrier
	s_add_i32 s60, s50, s33
	v_lshl_add_u64 v[170:171], s[34:35], 0, v[146:147]
	s_mov_b32 m0, s60
	ds_read_b128 v[188:191], v177 offset:16384
	ds_read_b128 v[192:195], v177 offset:17408
	ds_read_b128 v[198:201], v177 offset:18432
	ds_read_b128 v[202:205], v177 offset:19456
	ds_read_b128 v[206:209], v177 offset:20480
	ds_read_b128 v[210:213], v177 offset:21504
	ds_read_b128 v[214:217], v177 offset:22528
	ds_read_b128 v[218:221], v177 offset:23552
	global_load_lds_dwordx4 v[170:171], off
	s_add_i32 m0, s60, 0x2000
	s_add_u32 s60, s34, 0x40000
	v_lshl_add_u64 v[196:197], s[34:35], 0, v[150:151]
	s_addc_u32 s61, s35, 0
	s_add_i32 s62, s51, s33
	global_load_lds_dwordx4 v[196:197], off
	v_lshl_add_u64 v[222:223], s[60:61], 0, v[146:147]
	s_mov_b32 m0, s62
	v_lshl_add_u64 v[224:225], s[36:37], 0, v[148:149]
	global_load_lds_dwordx4 v[222:223], off
	v_lshl_add_u64 v[222:223], s[60:61], 0, v[150:151]
	s_add_i32 m0, s62, 0x2000
	s_nop 0
	global_load_lds_dwordx4 v[222:223], off
	v_lshl_add_u64 v[222:223], s[36:37], 0, v[144:145]
	s_mov_b32 m0, s76
	s_nop 0
	global_load_lds_dwordx4 v[222:223], off
	s_mov_b32 m0, s38
	s_nop 0
	global_load_lds_dwordx4 v[224:225], off
	s_waitcnt vmcnt(8)
	s_waitcnt lgkmcnt(0)
	s_barrier
	s_setprio 1
	s_waitcnt lgkmcnt(0)
	v_mfma_f32_16x16x32_bf16 v[60:63], v[72:75], v[188:191], 0
	v_mfma_f32_16x16x32_bf16 v[56:59], v[88:91], v[188:191], 0
	v_mfma_f32_16x16x32_bf16 v[44:47], v[72:75], v[198:201], 0
	v_mfma_f32_16x16x32_bf16 v[40:43], v[88:91], v[198:201], 0
	v_mfma_f32_16x16x32_bf16 v[28:31], v[72:75], v[206:209], 0
	v_mfma_f32_16x16x32_bf16 v[24:27], v[88:91], v[206:209], 0
	v_mfma_f32_16x16x32_bf16 v[12:15], v[72:75], v[214:217], 0
	v_mfma_f32_16x16x32_bf16 v[8:11], v[88:91], v[214:217], 0
	v_mfma_f32_16x16x32_bf16 v[60:63], v[76:79], v[192:195], v[60:63]
	v_mfma_f32_16x16x32_bf16 v[56:59], v[92:95], v[192:195], v[56:59]
	v_mfma_f32_16x16x32_bf16 v[44:47], v[76:79], v[202:205], v[44:47]
	v_mfma_f32_16x16x32_bf16 v[40:43], v[92:95], v[202:205], v[40:43]
	v_mfma_f32_16x16x32_bf16 v[28:31], v[76:79], v[210:213], v[28:31]
	v_mfma_f32_16x16x32_bf16 v[24:27], v[92:95], v[210:213], v[24:27]
	v_mfma_f32_16x16x32_bf16 v[12:15], v[76:79], v[218:221], v[12:15]
	v_mfma_f32_16x16x32_bf16 v[8:11], v[92:95], v[218:221], v[8:11]
	s_setprio 0
	s_setprio 1
	v_mfma_f32_16x16x32_bf16 v[52:55], v[162:165], v[188:191], 0
	v_mfma_f32_16x16x32_bf16 v[48:51], v[180:183], v[188:191], 0
	v_mfma_f32_16x16x32_bf16 v[36:39], v[162:165], v[198:201], 0
	v_mfma_f32_16x16x32_bf16 v[32:35], v[180:183], v[198:201], 0
	v_mfma_f32_16x16x32_bf16 v[20:23], v[162:165], v[206:209], 0
	v_mfma_f32_16x16x32_bf16 v[16:19], v[180:183], v[206:209], 0
	v_mfma_f32_16x16x32_bf16 v[4:7], v[162:165], v[214:217], 0
	v_mfma_f32_16x16x32_bf16 v[0:3], v[180:183], v[214:217], 0
	v_mfma_f32_16x16x32_bf16 v[52:55], v[166:169], v[192:195], v[52:55]
	v_mfma_f32_16x16x32_bf16 v[48:51], v[184:187], v[192:195], v[48:51]
	v_mfma_f32_16x16x32_bf16 v[36:39], v[166:169], v[202:205], v[36:39]
	v_mfma_f32_16x16x32_bf16 v[32:35], v[184:187], v[202:205], v[32:35]
	v_mfma_f32_16x16x32_bf16 v[20:23], v[166:169], v[210:213], v[20:23]
	v_mfma_f32_16x16x32_bf16 v[16:19], v[184:187], v[210:213], v[16:19]
	v_mfma_f32_16x16x32_bf16 v[4:7], v[166:169], v[218:221], v[4:7]
	v_mfma_f32_16x16x32_bf16 v[0:3], v[184:187], v[218:221], v[0:3]
	s_setprio 0
	s_barrier
	s_branch .Lmid_p1

.Lmid_p1:
	s_add_i32 s60, 0, 0x18000
	s_add_i32 s61, 0, 0x1c000
	v_add_u32_e32 v92, s60, v173
	v_add_u32_e32 v152, s61, v173
	ds_read_b128 v[72:75], v92
	ds_read_b128 v[76:79], v92 offset:1024
	ds_read_b128 v[88:91], v92 offset:2048
	ds_read_b128 v[92:95], v92 offset:3072
	ds_read_b128 v[162:165], v152
	ds_read_b128 v[166:169], v152 offset:1024
	ds_read_b128 v[180:183], v152 offset:2048
	ds_read_b128 v[184:187], v152 offset:3072
	s_add_u32 s36, s36, 0x40000
	s_addc_u32 s37, s37, 0
	s_mov_b32 m0, s39
	v_lshl_add_u64 v[226:227], s[36:37], 0, v[144:145]
	ds_read_b128 v[188:191], v177 offset:32768
	ds_read_b128 v[192:195], v177 offset:33792
	ds_read_b128 v[198:201], v177 offset:34816
	ds_read_b128 v[202:205], v177 offset:35840
	ds_read_b128 v[206:209], v177 offset:36864
	ds_read_b128 v[210:213], v177 offset:37888
	ds_read_b128 v[214:217], v177 offset:38912
	ds_read_b128 v[218:221], v177 offset:39936
	global_load_lds_dwordx4 v[226:227], off
	v_lshl_add_u64 v[226:227], s[36:37], 0, v[148:149]
	s_mov_b32 m0, s40
	s_nop 0
	global_load_lds_dwordx4 v[226:227], off
	s_waitcnt vmcnt(8)
	s_waitcnt lgkmcnt(0)
	s_barrier
	s_setprio 1
	s_waitcnt lgkmcnt(0)
	v_mfma_f32_16x16x32_bf16 v[140:143], v[72:75], v[188:191], v[140:143]
	v_mfma_f32_16x16x32_bf16 v[136:139], v[88:91], v[188:191], v[136:139]
	v_mfma_f32_16x16x32_bf16 v[124:127], v[72:75], v[198:201], v[124:127]
	v_mfma_f32_16x16x32_bf16 v[120:123], v[88:91], v[198:201], v[120:123]
	v_mfma_f32_16x16x32_bf16 v[108:111], v[72:75], v[206:209], v[108:111]
	v_mfma_f32_16x16x32_bf16 v[104:107], v[88:91], v[206:209], v[104:107]
	v_mfma_f32_16x16x32_bf16 v[84:87], v[72:75], v[214:217], v[84:87]
	v_mfma_f32_16x16x32_bf16 v[80:83], v[88:91], v[214:217], v[80:83]
	v_mfma_f32_16x16x32_bf16 v[140:143], v[76:79], v[192:195], v[140:143]
	v_mfma_f32_16x16x32_bf16 v[136:139], v[92:95], v[192:195], v[136:139]
	v_mfma_f32_16x16x32_bf16 v[124:127], v[76:79], v[202:205], v[124:127]
	v_mfma_f32_16x16x32_bf16 v[120:123], v[92:95], v[202:205], v[120:123]
	v_mfma_f32_16x16x32_bf16 v[108:111], v[76:79], v[210:213], v[108:111]
	v_mfma_f32_16x16x32_bf16 v[104:107], v[92:95], v[210:213], v[104:107]
	v_mfma_f32_16x16x32_bf16 v[84:87], v[76:79], v[218:221], v[84:87]
	v_mfma_f32_16x16x32_bf16 v[80:83], v[92:95], v[218:221], v[80:83]
	s_setprio 0
	s_setprio 1
	v_mfma_f32_16x16x32_bf16 v[132:135], v[162:165], v[188:191], v[132:135]
	v_mfma_f32_16x16x32_bf16 v[128:131], v[180:183], v[188:191], v[128:131]
	v_mfma_f32_16x16x32_bf16 v[116:119], v[162:165], v[198:201], v[116:119]
	v_mfma_f32_16x16x32_bf16 v[112:115], v[180:183], v[198:201], v[112:115]
	v_mfma_f32_16x16x32_bf16 v[100:103], v[162:165], v[206:209], v[100:103]
	v_mfma_f32_16x16x32_bf16 v[96:99], v[180:183], v[206:209], v[96:99]
	v_mfma_f32_16x16x32_bf16 v[68:71], v[162:165], v[214:217], v[68:71]
	v_mfma_f32_16x16x32_bf16 v[64:67], v[180:183], v[214:217], v[64:67]
	v_mfma_f32_16x16x32_bf16 v[132:135], v[166:169], v[192:195], v[132:135]
	v_mfma_f32_16x16x32_bf16 v[128:131], v[184:187], v[192:195], v[128:131]
	v_mfma_f32_16x16x32_bf16 v[116:119], v[166:169], v[202:205], v[116:119]
	v_mfma_f32_16x16x32_bf16 v[112:115], v[184:187], v[202:205], v[112:115]
	v_mfma_f32_16x16x32_bf16 v[100:103], v[166:169], v[210:213], v[100:103]
	v_mfma_f32_16x16x32_bf16 v[96:99], v[184:187], v[210:213], v[96:99]
	v_mfma_f32_16x16x32_bf16 v[68:71], v[166:169], v[218:221], v[68:71]
	v_mfma_f32_16x16x32_bf16 v[64:67], v[184:187], v[218:221], v[64:67]
	s_setprio 0
	s_barrier
	s_add_i32 s36, s60, s33
	v_lshl_add_u64 v[170:171], v[170:171], 0, s[18:19]
	s_mov_b32 m0, s36
	ds_read_b128 v[188:191], v177 offset:49152
	ds_read_b128 v[192:195], v177 offset:50176
	ds_read_b128 v[198:201], v177 offset:51200
	ds_read_b128 v[202:205], v177 offset:52224
	ds_read_b128 v[206:209], v177 offset:53248
	ds_read_b128 v[210:213], v177 offset:54272
	ds_read_b128 v[214:217], v177 offset:55296
	ds_read_b128 v[218:221], v177 offset:56320
	global_load_lds_dwordx4 v[170:171], off
	s_add_i32 m0, s36, 0x2000
	s_add_u32 s34, s34, 0x40080
	v_lshl_add_u64 v[170:171], v[196:197], 0, s[18:19]
	s_addc_u32 s35, s35, 0
	s_add_i32 s36, s61, s33
	global_load_lds_dwordx4 v[170:171], off
	v_lshl_add_u64 v[170:171], s[34:35], 0, v[146:147]
	s_mov_b32 m0, s36
	s_nop 0
	global_load_lds_dwordx4 v[170:171], off
	v_lshl_add_u64 v[170:171], s[34:35], 0, v[150:151]
	s_add_i32 m0, s36, 0x2000
	s_nop 0
	global_load_lds_dwordx4 v[170:171], off
	v_lshl_add_u64 v[170:171], v[222:223], 0, s[18:19]
	s_mov_b32 m0, s42
	s_nop 0
	global_load_lds_dwordx4 v[170:171], off
	v_lshl_add_u64 v[170:171], v[224:225], 0, s[18:19]
	s_mov_b32 m0, s43
	s_nop 0
	global_load_lds_dwordx4 v[170:171], off
	s_waitcnt vmcnt(8)
	s_waitcnt lgkmcnt(0)
	s_barrier
	s_setprio 1
	s_waitcnt lgkmcnt(0)
	v_mfma_f32_16x16x32_bf16 v[60:63], v[72:75], v[188:191], v[60:63]
	v_mfma_f32_16x16x32_bf16 v[56:59], v[88:91], v[188:191], v[56:59]
	v_mfma_f32_16x16x32_bf16 v[44:47], v[72:75], v[198:201], v[44:47]
	v_mfma_f32_16x16x32_bf16 v[40:43], v[88:91], v[198:201], v[40:43]
	v_mfma_f32_16x16x32_bf16 v[28:31], v[72:75], v[206:209], v[28:31]
	v_mfma_f32_16x16x32_bf16 v[24:27], v[88:91], v[206:209], v[24:27]
	v_mfma_f32_16x16x32_bf16 v[12:15], v[72:75], v[214:217], v[12:15]
	v_mfma_f32_16x16x32_bf16 v[8:11], v[88:91], v[214:217], v[8:11]
	v_mfma_f32_16x16x32_bf16 v[60:63], v[76:79], v[192:195], v[60:63]
	v_mfma_f32_16x16x32_bf16 v[56:59], v[92:95], v[192:195], v[56:59]
	v_mfma_f32_16x16x32_bf16 v[44:47], v[76:79], v[202:205], v[44:47]
	v_mfma_f32_16x16x32_bf16 v[40:43], v[92:95], v[202:205], v[40:43]
	v_mfma_f32_16x16x32_bf16 v[28:31], v[76:79], v[210:213], v[28:31]
	v_mfma_f32_16x16x32_bf16 v[24:27], v[92:95], v[210:213], v[24:27]
	v_mfma_f32_16x16x32_bf16 v[12:15], v[76:79], v[218:221], v[12:15]
	v_mfma_f32_16x16x32_bf16 v[8:11], v[92:95], v[218:221], v[8:11]
	s_setprio 0
	s_setprio 1
	v_mfma_f32_16x16x32_bf16 v[52:55], v[162:165], v[188:191], v[52:55]
	v_mfma_f32_16x16x32_bf16 v[48:51], v[180:183], v[188:191], v[48:51]
	v_mfma_f32_16x16x32_bf16 v[36:39], v[162:165], v[198:201], v[36:39]
	v_mfma_f32_16x16x32_bf16 v[32:35], v[180:183], v[198:201], v[32:35]
	v_mfma_f32_16x16x32_bf16 v[20:23], v[162:165], v[206:209], v[20:23]
	v_mfma_f32_16x16x32_bf16 v[16:19], v[180:183], v[206:209], v[16:19]
	v_mfma_f32_16x16x32_bf16 v[4:7], v[162:165], v[214:217], v[4:7]
	v_mfma_f32_16x16x32_bf16 v[0:3], v[180:183], v[214:217], v[0:3]
	v_mfma_f32_16x16x32_bf16 v[52:55], v[166:169], v[192:195], v[52:55]
	v_mfma_f32_16x16x32_bf16 v[48:51], v[184:187], v[192:195], v[48:51]
	v_mfma_f32_16x16x32_bf16 v[36:39], v[166:169], v[202:205], v[36:39]
	v_mfma_f32_16x16x32_bf16 v[32:35], v[184:187], v[202:205], v[32:35]
	v_mfma_f32_16x16x32_bf16 v[20:23], v[166:169], v[210:213], v[20:23]
	v_mfma_f32_16x16x32_bf16 v[16:19], v[184:187], v[210:213], v[16:19]
	v_mfma_f32_16x16x32_bf16 v[4:7], v[166:169], v[218:221], v[4:7]
	v_mfma_f32_16x16x32_bf16 v[0:3], v[184:187], v[218:221], v[0:3]
	s_setprio 0
	s_barrier
	s_add_i32 s59, s59, 2
	s_add_u32 s30, s30, 0x100
	s_addc_u32 s31, s31, 0
	s_add_u32 s57, s57, 0x100
	s_addc_u32 s58, s58, 0
	s_cmp_gt_u32 s59, 13
	s_cbranch_scc0 .LBB0_120
	s_and_b64 vcc, exec, s[20:21]
	s_cbranch_vccz .LBB0_123
	s_barrier
